# layer-0 in-projection phase: workgroups 0..31 (memory tiles with the slow per-element epilogue) hand their third tile to workgroups 448..479 which had two
# speedup vs baseline: 1.0181x; 1.0005x over previous
; __global__ void __launch_bounds__(256, 2) fwd_megakernel(Params p) {
;     ...
;     for (int t = blockIdx.x; t < n_mem + n_proj; t += gridDim.x) {
;       f32x16 acc[2][2];
;       if (t < n_mem) {
;         const int l = t >> 4, tm = (t >> 3) & 1, tn = t & 7;
.LBB0_164:
	s_add_i32 s53, s53, s50
	s_add_i32 s39, s39, s40
	s_add_i32 s41, s41, s42
	s_cmpk_lg_u32 s50, 0x200
	s_cbranch_scc1 .Lp1_keep
	s_cmpk_lt_i32 s53, 0x400
	s_cbranch_scc1 .Lp1_keep
	s_cmpk_ge_i32 s53, 0x600
	s_cbranch_scc1 .Lp1_keep
	s_cmpk_lt_u32 s78, 32
	s_cbranch_scc0 .Lp1_a
	s_movk_i32 s53, 0x5c0
	s_branch .Lp1_keep
.Lp1_a:
	s_sub_u32 s98, s78, 0x1c0
	s_cmpk_lt_u32 s98, 32
	s_cbranch_scc0 .Lp1_keep
	s_add_u32 s53, s98, 0x400
	s_lshl_b32 s39, s53, 4
	s_lshl_b32 s41, s53, 7
.Lp1_keep:
	s_cmpk_gt_i32 s53, 0x5bf
	s_cbranch_scc1 .LBB0_424
